# phase F epilogue: adaLN gate vectors loaded once per tile instead of 16 serialized reloads
# baseline (speedup 1.0000x reference)
; #define EPI_FENCE(a, b) asm volatile("" : "+v"(a), "+v"(b) :: "memory")
;     __device__ __forceinline__ void operator()(const AccT& acc, const pg8::Unit& u, int wr, int wc, int fr, int fq) const {
;     ...
;             for (int i = 0; i < 4; ++i) { const int row = row0 + ai * 128 + (m0 + (i >> 1)) * 16, col0 = pn * 256 + (i & 1) * 128 + wc * 32 + 8 * fq;
;                 const float* xo = (layer == 0) ? (lat ? xin + (size_t)row * 2048 : ctxin + (size_t)(row - NLAT) * 2048) : xcur + (size_t)row * 2048;
;                 xa[i] = *(const f32x4*)(xo + col0); xb[i] = *(const f32x4*)(xo + col0 + 4); }
; #pragma unroll
;             for (int i = 0; i < 4; ++i) { const int m = m0 + (i >> 1), bj = i & 1; const int row = row0 + ai * 128 + m * 16, col0 = pn * 256 + bj * 128 + wc * 32 + 8 * fq;
;                 f32x4 v0 = acc[ai][bj][m][0], v1 = acc[ai][bj][m][1]; EPI_FENCE(v0, v1);
;                 const f32x4 g0 = *(const f32x4*)(gt + col0), g1 = *(const f32x4*)(gt + col0 + 4);
;                 *(f32x4*)(xcur + (size_t)row * 2048 + col0) = xa[i] + g0 * v0;
;                 *(f32x4*)(xcur + (size_t)row * 2048 + col0 + 4) = xb[i] + g1 * v1; }
.LBB0_991:
	s_lshl_b64 s[28:29], s[28:29], 2
	s_add_u32 s19, s46, s28
	s_addc_u32 s21, s47, s29
	s_add_u32 s28, s19, 0x13c04000
	s_addc_u32 s29, s21, 0
	v_add_u32_e32 v174, 0x80, v164
	v_lshl_add_u64 v[164:165], v[172:173], 0, v[162:163]
	global_load_dwordx4 v[170:173], v[164:165], off offset:528
	global_load_dwordx4 v[180:183], v[164:165], off offset:512
	v_lshl_add_u64 v[164:165], s[28:29], 0, v[162:163]
	global_load_dwordx4 v[204:207], v[164:165], off offset:16
	global_load_dwordx4 v[200:203], v[164:165], off
	v_ashrrev_i32_e32 v167, 31, v166
	v_ashrrev_i32_e32 v175, 31, v174
	v_lshl_add_u64 v[216:217], v[174:175], 2, s[28:29]
	global_load_dwordx4 v[212:215], v[216:217], off offset:16
	global_load_dwordx4 v[208:211], v[216:217], off
	s_and_b64 vcc, exec, s[8:9]
	s_waitcnt vmcnt(0)
	v_pk_fma_f32 v[122:123], v[122:123], v[206:207], v[146:147]
	v_pk_fma_f32 v[124:125], v[200:201], v[124:125], v[148:149]
	v_lshlrev_b64 v[148:149], 13, v[166:167]
	v_lshl_add_u64 v[148:149], s[12:13], 0, v[148:149]
	v_pk_fma_f32 v[126:127], v[202:203], v[126:127], v[150:151]
	v_lshl_add_u64 v[148:149], v[148:149], 0, v[162:163]
	v_pk_fma_f32 v[120:121], v[120:121], v[204:205], v[144:145]
	global_store_dwordx4 v[148:149], v[124:127], off
	global_store_dwordx4 v[148:149], v[120:123], off offset:16
	s_nop 0
	v_or_b32_e32 v126, 48, v166
	v_lshl_add_u64 v[120:121], v[174:175], 2, s[28:29]
	s_mov_b64 s[28:29], -1
	v_ashrrev_i32_e32 v127, 31, v126
	v_pk_fma_f32 v[110:111], v[110:111], v[214:215], v[138:139]
	v_pk_fma_f32 v[118:119], v[210:211], v[118:119], v[142:143]
	v_pk_fma_f32 v[116:117], v[208:209], v[116:117], v[140:141]
	v_pk_fma_f32 v[108:109], v[108:109], v[212:213], v[136:137]
	global_store_dwordx4 v[148:149], v[116:119], off offset:512
	global_store_dwordx4 v[148:149], v[108:111], off offset:528
	v_or_b32_e32 v122, 32, v166
	v_pk_fma_f32 v[106:107], v[106:107], v[206:207], v[130:131]
	v_pk_fma_f32 v[112:113], v[200:201], v[112:113], v[132:133]
	v_lshl_add_u64 v[116:117], s[12:13], 0, v[168:169]
	v_pk_fma_f32 v[114:115], v[202:203], v[114:115], v[134:135]
	v_lshl_add_u64 v[116:117], v[116:117], 0, v[162:163]
	v_pk_fma_f32 v[104:105], v[104:105], v[204:205], v[128:129]
	global_store_dwordx4 v[116:117], v[112:115], off
	global_store_dwordx4 v[116:117], v[104:107], off offset:16
	v_add_u32_e32 v128, 0xffffc030, v166
	v_pk_fma_f32 v[98:99], v[98:99], v[214:215], v[172:173]
	v_pk_fma_f32 v[96:97], v[96:97], v[212:213], v[170:171]
	global_store_dwordx4 v[116:117], v[96:99], off offset:528
	v_pk_fma_f32 v[100:101], v[208:209], v[100:101], v[180:181]
	v_cndmask_b32_e64 v108, v128, v126, s[10:11]
	v_add_u32_e32 v96, 0xffffc020, v166
	v_cndmask_b32_e64 v96, v96, v122, s[10:11]
	v_cndmask_b32_e64 v96, v122, v96, s[2:3]
	v_ashrrev_i32_e32 v97, 31, v96
	v_lshlrev_b64 v[96:97], 13, v[96:97]
	v_cndmask_b32_e64 v108, v126, v108, s[2:3]
	v_pk_fma_f32 v[102:103], v[210:211], v[102:103], v[182:183]
	v_lshl_add_u64 v[96:97], s[26:27], 0, v[96:97]
	v_ashrrev_i32_e32 v109, 31, v108
	global_store_dwordx4 v[116:117], v[100:103], off offset:512
	v_lshlrev_b64 v[108:109], 13, v[108:109]
	v_lshl_add_u64 v[108:109], s[26:27], 0, v[108:109]
	v_lshl_add_u64 v[100:101], v[96:97], 0, v[162:163]
	global_load_dwordx4 v[104:107], v[100:101], off offset:16
	global_load_dwordx4 v[116:119], v[100:101], off
	global_load_dwordx4 v[96:99], v[100:101], off offset:528
	s_nop 0
	global_load_dwordx4 v[100:103], v[100:101], off offset:512
	v_lshl_add_u64 v[112:113], v[108:109], 0, v[162:163]
	global_load_dwordx4 v[108:111], v[112:113], off offset:16
	s_nop 0
	global_load_dwordx4 v[112:115], v[112:113], off
	s_cbranch_vccnz .LBB0_993
	v_lshlrev_b64 v[124:125], 13, v[126:127]
	v_lshl_add_u64 v[130:131], s[12:13], 0, v[124:125]
	s_mov_b64 s[28:29], 0

; #define EPI_FENCE(a, b) asm volatile("" : "+v"(a), "+v"(b) :: "memory")
;     __device__ __forceinline__ void operator()(const AccT& acc, const pg8::Unit& u, int wr, int wc, int fr, int fq) const {
;     ...
; #pragma unroll
;             for (int i = 0; i < 4; ++i) { const int m = m0 + (i >> 1), bj = i & 1; const int row = row0 + ai * 128 + m * 16, col0 = pn * 256 + bj * 128 + wc * 32 + 8 * fq;
;                 f32x4 v0 = acc[ai][bj][m][0], v1 = acc[ai][bj][m][1]; EPI_FENCE(v0, v1);
;                 const f32x4 g0 = *(const f32x4*)(gt + col0), g1 = *(const f32x4*)(gt + col0 + 4);
;                 *(f32x4*)(xcur + (size_t)row * 2048 + col0) = xa[i] + g0 * v0;
;                 *(f32x4*)(xcur + (size_t)row * 2048 + col0 + 4) = xb[i] + g1 * v1; }
.LBB0_998:
	v_lshl_add_u64 v[130:131], v[130:131], 0, v[162:163]
	global_load_dwordx4 v[126:129], v[130:131], off offset:528
	s_nop 0
	global_load_dwordx4 v[130:133], v[130:131], off offset:512
	v_ashrrev_i32_e32 v123, 31, v122
	s_mov_b64 s[28:29], -1
	s_and_b64 vcc, exec, s[8:9]
	s_waitcnt vmcnt(0)
	v_pk_fma_f32 v[88:89], v[88:89], v[204:205], v[104:105]
	v_pk_fma_f32 v[92:93], v[200:201], v[92:93], v[116:117]
	v_lshlrev_b64 v[116:117], 13, v[122:123]
	v_lshl_add_u64 v[116:117], s[12:13], 0, v[116:117]
	v_pk_fma_f32 v[94:95], v[202:203], v[94:95], v[118:119]
	v_lshl_add_u64 v[116:117], v[116:117], 0, v[162:163]
	v_pk_fma_f32 v[90:91], v[90:91], v[206:207], v[106:107]
	global_store_dwordx4 v[116:117], v[92:95], off
	global_store_dwordx4 v[116:117], v[88:91], off offset:16
	v_pk_fma_f32 v[76:77], v[76:77], v[212:213], v[96:97]
	v_pk_fma_f32 v[86:87], v[210:211], v[86:87], v[102:103]
	v_pk_fma_f32 v[84:85], v[208:209], v[84:85], v[100:101]
	v_pk_fma_f32 v[78:79], v[78:79], v[214:215], v[98:99]
	global_store_dwordx4 v[116:117], v[84:87], off offset:512
	global_store_dwordx4 v[116:117], v[76:79], off offset:528
	v_add_u32_e32 v88, 0x80, v166
	v_add_u32_e32 v92, 0x90, v166
	v_add_u32_e32 v94, 0xffffc090, v166
	v_ashrrev_i32_e32 v93, 31, v92
	v_pk_fma_f32 v[72:73], v[72:73], v[204:205], v[108:109]
	v_pk_fma_f32 v[80:81], v[200:201], v[80:81], v[112:113]
	v_lshl_add_u64 v[84:85], s[12:13], 0, v[124:125]
	v_pk_fma_f32 v[82:83], v[202:203], v[82:83], v[114:115]
	v_lshl_add_u64 v[84:85], v[84:85], 0, v[162:163]
	v_pk_fma_f32 v[74:75], v[74:75], v[206:207], v[110:111]
	global_store_dwordx4 v[84:85], v[80:83], off
	global_store_dwordx4 v[84:85], v[72:75], off offset:16
	v_pk_fma_f32 v[66:67], v[66:67], v[214:215], v[128:129]
	v_pk_fma_f32 v[64:65], v[64:65], v[212:213], v[126:127]
	global_store_dwordx4 v[84:85], v[64:67], off offset:528
	v_pk_fma_f32 v[68:69], v[208:209], v[68:69], v[130:131]
	v_cndmask_b32_e64 v76, v94, v92, s[10:11]
	v_add_u32_e32 v64, 0xffffc080, v166
	v_cndmask_b32_e64 v64, v64, v88, s[10:11]
	v_cndmask_b32_e64 v64, v88, v64, s[2:3]
	v_ashrrev_i32_e32 v65, 31, v64
	v_lshlrev_b64 v[64:65], 13, v[64:65]
	v_cndmask_b32_e64 v76, v92, v76, s[2:3]
	v_pk_fma_f32 v[70:71], v[210:211], v[70:71], v[132:133]
	v_lshl_add_u64 v[64:65], s[26:27], 0, v[64:65]
	v_ashrrev_i32_e32 v77, 31, v76
	global_store_dwordx4 v[84:85], v[68:71], off offset:512
	v_lshlrev_b64 v[76:77], 13, v[76:77]
	v_lshl_add_u64 v[76:77], s[26:27], 0, v[76:77]
	v_lshl_add_u64 v[68:69], v[64:65], 0, v[162:163]
	global_load_dwordx4 v[72:75], v[68:69], off offset:16
	global_load_dwordx4 v[84:87], v[68:69], off
	global_load_dwordx4 v[64:67], v[68:69], off offset:528
	s_nop 0
	global_load_dwordx4 v[68:71], v[68:69], off offset:512
	v_lshl_add_u64 v[80:81], v[76:77], 0, v[162:163]
	global_load_dwordx4 v[76:79], v[80:81], off offset:16
	s_nop 0
	global_load_dwordx4 v[80:83], v[80:81], off
	s_cbranch_vccnz .LBB0_1000
	v_lshlrev_b64 v[90:91], 13, v[92:93]
	v_lshl_add_u64 v[96:97], s[12:13], 0, v[90:91]
	s_mov_b64 s[28:29], 0

; #define EPI_FENCE(a, b) asm volatile("" : "+v"(a), "+v"(b) :: "memory")
;     __device__ __forceinline__ void operator()(const AccT& acc, const pg8::Unit& u, int wr, int wc, int fr, int fq) const {
;     ...
; #pragma unroll
;             for (int i = 0; i < 4; ++i) { const int m = m0 + (i >> 1), bj = i & 1; const int row = row0 + ai * 128 + m * 16, col0 = pn * 256 + bj * 128 + wc * 32 + 8 * fq;
;                 f32x4 v0 = acc[ai][bj][m][0], v1 = acc[ai][bj][m][1]; EPI_FENCE(v0, v1);
;                 const f32x4 g0 = *(const f32x4*)(gt + col0), g1 = *(const f32x4*)(gt + col0 + 4);
;                 *(f32x4*)(xcur + (size_t)row * 2048 + col0) = xa[i] + g0 * v0;
;                 *(f32x4*)(xcur + (size_t)row * 2048 + col0 + 4) = xb[i] + g1 * v1; }
.LBB0_1005:
	v_lshl_add_u64 v[96:97], v[96:97], 0, v[162:163]
	global_load_dwordx4 v[92:95], v[96:97], off offset:528
	s_nop 0
	global_load_dwordx4 v[96:99], v[96:97], off offset:512
	v_ashrrev_i32_e32 v89, 31, v88
	s_and_b64 vcc, exec, s[8:9]
	s_waitcnt vmcnt(0)
	v_pk_fma_f32 v[56:57], v[56:57], v[204:205], v[72:73]
	v_pk_fma_f32 v[60:61], v[200:201], v[60:61], v[84:85]
	v_lshlrev_b64 v[84:85], 13, v[88:89]
	v_lshl_add_u64 v[84:85], s[12:13], 0, v[84:85]
	v_pk_fma_f32 v[62:63], v[202:203], v[62:63], v[86:87]
	v_lshl_add_u64 v[84:85], v[84:85], 0, v[162:163]
	v_pk_fma_f32 v[58:59], v[58:59], v[206:207], v[74:75]
	global_store_dwordx4 v[84:85], v[60:63], off
	global_store_dwordx4 v[84:85], v[56:59], off offset:16
	v_pk_fma_f32 v[44:45], v[44:45], v[212:213], v[64:65]
	v_pk_fma_f32 v[54:55], v[210:211], v[54:55], v[70:71]
	v_pk_fma_f32 v[52:53], v[208:209], v[52:53], v[68:69]
	v_pk_fma_f32 v[46:47], v[46:47], v[214:215], v[66:67]
	global_store_dwordx4 v[84:85], v[52:55], off offset:512
	global_store_dwordx4 v[84:85], v[44:47], off offset:528
	v_add_u32_e32 v56, 0xa0, v166
	v_add_u32_e32 v60, 0xb0, v166
	v_add_u32_e32 v62, 0xffffc0b0, v166
	v_ashrrev_i32_e32 v61, 31, v60
	v_pk_fma_f32 v[40:41], v[40:41], v[204:205], v[76:77]
	v_pk_fma_f32 v[48:49], v[200:201], v[48:49], v[80:81]
	v_lshl_add_u64 v[52:53], s[12:13], 0, v[90:91]
	v_pk_fma_f32 v[50:51], v[202:203], v[50:51], v[82:83]
	v_lshl_add_u64 v[52:53], v[52:53], 0, v[162:163]
	v_pk_fma_f32 v[42:43], v[42:43], v[206:207], v[78:79]
	global_store_dwordx4 v[52:53], v[48:51], off
	global_store_dwordx4 v[52:53], v[40:43], off offset:16
	v_cndmask_b32_e64 v48, v62, v60, s[10:11]
	v_cndmask_b32_e64 v48, v60, v48, s[2:3]
	v_ashrrev_i32_e32 v49, 31, v48
	v_lshlrev_b64 v[48:49], 13, v[48:49]
	v_lshl_add_u64 v[48:49], s[26:27], 0, v[48:49]
	v_pk_fma_f32 v[34:35], v[34:35], v[214:215], v[94:95]
	v_pk_fma_f32 v[32:33], v[32:33], v[212:213], v[92:93]
	global_store_dwordx4 v[52:53], v[32:35], off offset:528
	v_pk_fma_f32 v[38:39], v[210:211], v[38:39], v[98:99]
	v_pk_fma_f32 v[36:37], v[208:209], v[36:37], v[96:97]
	v_add_u32_e32 v32, 0xffffc0a0, v166
	v_cndmask_b32_e64 v32, v32, v56, s[10:11]
	v_cndmask_b32_e64 v32, v56, v32, s[2:3]
	v_ashrrev_i32_e32 v33, 31, v32
	v_lshlrev_b64 v[32:33], 13, v[32:33]
	v_lshl_add_u64 v[32:33], s[26:27], 0, v[32:33]
	global_store_dwordx4 v[52:53], v[36:39], off offset:512
	v_lshl_add_u64 v[52:53], v[48:49], 0, v[162:163]
	s_mov_b64 s[10:11], -1
	v_lshl_add_u64 v[36:37], v[32:33], 0, v[162:163]
	global_load_dwordx4 v[40:43], v[36:37], off offset:16
	global_load_dwordx4 v[44:47], v[36:37], off
	global_load_dwordx4 v[32:35], v[36:37], off offset:528
	s_nop 0
	global_load_dwordx4 v[36:39], v[36:37], off offset:512
	s_nop 0
	global_load_dwordx4 v[48:51], v[52:53], off offset:16
	s_nop 0
	global_load_dwordx4 v[52:55], v[52:53], off
	s_cbranch_vccnz .LBB0_1007
	v_lshlrev_b64 v[58:59], 13, v[60:61]
	v_lshl_add_u64 v[64:65], s[12:13], 0, v[58:59]
	s_mov_b64 s[10:11], 0

; #define EPI_FENCE(a, b) asm volatile("" : "+v"(a), "+v"(b) :: "memory")
;     __device__ __forceinline__ void operator()(const AccT& acc, const pg8::Unit& u, int wr, int wc, int fr, int fq) const {
;     ...
; #pragma unroll
;             for (int i = 0; i < 4; ++i) { const int m = m0 + (i >> 1), bj = i & 1; const int row = row0 + ai * 128 + m * 16, col0 = pn * 256 + bj * 128 + wc * 32 + 8 * fq;
;                 f32x4 v0 = acc[ai][bj][m][0], v1 = acc[ai][bj][m][1]; EPI_FENCE(v0, v1);
;                 const f32x4 g0 = *(const f32x4*)(gt + col0), g1 = *(const f32x4*)(gt + col0 + 4);
;                 *(f32x4*)(xcur + (size_t)row * 2048 + col0) = xa[i] + g0 * v0;
;                 *(f32x4*)(xcur + (size_t)row * 2048 + col0 + 4) = xb[i] + g1 * v1; }
.LBB0_1012:
	v_lshl_add_u64 v[64:65], v[64:65], 0, v[162:163]
	global_load_dwordx4 v[60:63], v[64:65], off offset:528
	s_nop 0
	global_load_dwordx4 v[64:67], v[64:65], off offset:512
	v_ashrrev_i32_e32 v57, 31, v56
	v_lshlrev_b64 v[56:57], 13, v[56:57]
	v_lshl_add_u64 v[56:57], s[12:13], 0, v[56:57]
	v_lshl_add_u64 v[56:57], v[56:57], 0, v[162:163]
	s_andn2_b64 vcc, exec, s[4:5]
	s_mov_b64 s[4:5], -1
	s_waitcnt vmcnt(0)
	v_pk_fma_f32 v[30:31], v[202:203], v[30:31], v[46:47]
	v_pk_fma_f32 v[28:29], v[200:201], v[28:29], v[44:45]
	v_pk_fma_f32 v[24:25], v[24:25], v[204:205], v[40:41]
	v_pk_fma_f32 v[26:27], v[26:27], v[206:207], v[42:43]
	global_store_dwordx4 v[56:57], v[28:31], off
	global_store_dwordx4 v[56:57], v[24:27], off offset:16
	v_pk_fma_f32 v[22:23], v[210:211], v[22:23], v[38:39]
	v_pk_fma_f32 v[20:21], v[208:209], v[20:21], v[36:37]
	v_pk_fma_f32 v[12:13], v[12:13], v[212:213], v[32:33]
	v_pk_fma_f32 v[14:15], v[14:15], v[214:215], v[34:35]
	global_store_dwordx4 v[56:57], v[20:23], off offset:512
	global_store_dwordx4 v[56:57], v[12:15], off offset:528
	v_lshl_add_u64 v[24:25], s[12:13], 0, v[58:59]
	v_lshl_add_u64 v[24:25], v[24:25], 0, v[162:163]
	v_pk_fma_f32 v[14:15], v[202:203], v[18:19], v[54:55]
	v_pk_fma_f32 v[12:13], v[200:201], v[16:17], v[52:53]
	v_pk_fma_f32 v[8:9], v[8:9], v[204:205], v[48:49]
	v_pk_fma_f32 v[10:11], v[10:11], v[206:207], v[50:51]
	global_store_dwordx4 v[24:25], v[12:15], off
	global_store_dwordx4 v[24:25], v[8:11], off offset:16
	v_pk_fma_f32 v[6:7], v[210:211], v[6:7], v[66:67]
	v_pk_fma_f32 v[4:5], v[208:209], v[4:5], v[64:65]
	v_pk_fma_f32 v[2:3], v[2:3], v[214:215], v[62:63]
	v_pk_fma_f32 v[0:1], v[0:1], v[212:213], v[60:61]
	global_store_dwordx4 v[24:25], v[4:7], off offset:512
	global_store_dwordx4 v[24:25], v[0:3], off offset:528
	s_cbranch_vccnz .LBB0_974
	s_andn2_b64 vcc, exec, s[0:1]
	s_cbranch_vccnz .LBB0_973
	s_barrier
	s_branch .LBB0_973
